# NSA importance reduction: lane^8 via DPP row_ror:8 and lane^16 via v_permlane16_swap instead of 64 serialized ds_bpermute round trips per item (same operations and order)
# speedup vs baseline: 1.0228x; 1.0050x over previous
.LBB0_244:
	v_mov_b32_e32 v0, v222
	s_waitcnt lgkmcnt(0)
	s_barrier
	s_nop 0
	v_lshlrev_b32_e32 v0, 2, v0
	v_xor_b32_e32 v0, 0x80, v0
	ds_bpermute_b32 v0, v0, v187
	s_waitcnt lgkmcnt(0)
	v_add_f32_e32 v0, v187, v0
	v_div_scale_f32 v66, s[0:1], v0, v0, 1.0
	v_rcp_f32_e32 v67, v66
	v_div_scale_f32 v68, vcc, 1.0, v0, 1.0
	v_fma_f32 v69, -v66, v67, 1.0
	v_fmac_f32_e32 v67, v69, v67
	v_mul_f32_e32 v69, v68, v67
	v_fma_f32 v70, -v66, v69, v68
	v_fmac_f32_e32 v69, v70, v67
	v_fma_f32 v66, -v66, v69, v68
	v_div_fmas_f32 v66, v66, v67, v69
	v_div_fixup_f32 v66, v66, v0, 1.0
	v_cmp_lt_f32_e32 vcc, 0, v0
	s_nop 1
	v_cndmask_b32_e32 v140, 0, v66, vcc
	v_mul_f32_e32 v0, v50, v140
	v_mul_f32_e32 v226, v51, v140
	v_mul_f32_e32 v227, v52, v140
	v_mov_b32_dpp v0, v0 row_ror:8 row_mask:0xf bank_mask:0xf
	v_mov_b32_dpp v226, v226 row_ror:8 row_mask:0xf bank_mask:0xf
	v_mov_b32_dpp v227, v227 row_ror:8 row_mask:0xf bank_mask:0xf
	v_fmac_f32_e32 v0, v50, v140
	v_fmac_f32_e32 v226, v51, v140
	v_fmac_f32_e32 v227, v52, v140
	v_mov_b32_e32 v50, v0
	v_mov_b32_e32 v51, v226
	v_mov_b32_e32 v52, v227
	v_permlane16_swap_b32_e32 v50, v0
	v_permlane16_swap_b32_e32 v51, v226
	v_permlane16_swap_b32_e32 v52, v227
	v_add_f32_e32 v0, v50, v0
	v_add_f32_e32 v226, v51, v226
	v_add_f32_e32 v227, v52, v227
	s_and_saveexec_b64 s[0:1], s[4:5]
	ds_write_b32 v177, v0 offset:36864
	ds_write_b32 v177, v226 offset:36868
	ds_write_b32 v177, v227 offset:36872
	s_or_b64 exec, exec, s[0:1]
	v_mul_f32_e32 v0, v53, v140
	v_mul_f32_e32 v226, v54, v140
	v_mul_f32_e32 v227, v55, v140
	v_mov_b32_dpp v0, v0 row_ror:8 row_mask:0xf bank_mask:0xf
	v_mov_b32_dpp v226, v226 row_ror:8 row_mask:0xf bank_mask:0xf
	v_mov_b32_dpp v227, v227 row_ror:8 row_mask:0xf bank_mask:0xf
	v_fmac_f32_e32 v0, v53, v140
	v_fmac_f32_e32 v226, v54, v140
	v_fmac_f32_e32 v227, v55, v140
	v_mov_b32_e32 v53, v0
	v_mov_b32_e32 v54, v226
	v_mov_b32_e32 v55, v227
	v_permlane16_swap_b32_e32 v53, v0
	v_permlane16_swap_b32_e32 v54, v226
	v_permlane16_swap_b32_e32 v55, v227
	v_add_f32_e32 v0, v53, v0
	v_add_f32_e32 v226, v54, v226
	v_add_f32_e32 v227, v55, v227
	s_and_saveexec_b64 s[0:1], s[4:5]
	ds_write_b32 v177, v0 offset:36876
	ds_write_b32 v177, v226 offset:36896
	ds_write_b32 v177, v227 offset:36900
	s_or_b64 exec, exec, s[0:1]
	v_mul_f32_e32 v0, v56, v140
	v_mul_f32_e32 v226, v57, v140
	v_mul_f32_e32 v227, v58, v140
	v_mov_b32_dpp v0, v0 row_ror:8 row_mask:0xf bank_mask:0xf
	v_mov_b32_dpp v226, v226 row_ror:8 row_mask:0xf bank_mask:0xf
	v_mov_b32_dpp v227, v227 row_ror:8 row_mask:0xf bank_mask:0xf
	v_fmac_f32_e32 v0, v56, v140
	v_fmac_f32_e32 v226, v57, v140
	v_fmac_f32_e32 v227, v58, v140
	v_mov_b32_e32 v56, v0
	v_mov_b32_e32 v57, v226
	v_mov_b32_e32 v58, v227
	v_permlane16_swap_b32_e32 v56, v0
	v_permlane16_swap_b32_e32 v57, v226
	v_permlane16_swap_b32_e32 v58, v227
	v_add_f32_e32 v0, v56, v0
	v_add_f32_e32 v226, v57, v226
	v_add_f32_e32 v227, v58, v227
	s_and_saveexec_b64 s[0:1], s[4:5]
	ds_write_b32 v177, v0 offset:36904
	ds_write_b32 v177, v226 offset:36908
	ds_write_b32 v177, v227 offset:36928
	s_or_b64 exec, exec, s[0:1]
	v_mul_f32_e32 v0, v59, v140
	v_mul_f32_e32 v226, v60, v140
	v_mul_f32_e32 v227, v61, v140
	v_mov_b32_dpp v0, v0 row_ror:8 row_mask:0xf bank_mask:0xf
	v_mov_b32_dpp v226, v226 row_ror:8 row_mask:0xf bank_mask:0xf
	v_mov_b32_dpp v227, v227 row_ror:8 row_mask:0xf bank_mask:0xf
	v_fmac_f32_e32 v0, v59, v140
	v_fmac_f32_e32 v226, v60, v140
	v_fmac_f32_e32 v227, v61, v140
	v_mov_b32_e32 v59, v0
	v_mov_b32_e32 v60, v226
	v_mov_b32_e32 v61, v227
	v_permlane16_swap_b32_e32 v59, v0
	v_permlane16_swap_b32_e32 v60, v226
	v_permlane16_swap_b32_e32 v61, v227
	v_add_f32_e32 v0, v59, v0
	v_add_f32_e32 v226, v60, v226
	v_add_f32_e32 v227, v61, v227
	s_and_saveexec_b64 s[0:1], s[4:5]
	ds_write_b32 v177, v0 offset:36932
	ds_write_b32 v177, v226 offset:36936
	ds_write_b32 v177, v227 offset:36940
	s_or_b64 exec, exec, s[0:1]
	v_mul_f32_e32 v0, v62, v140
	v_mul_f32_e32 v226, v63, v140
	v_mul_f32_e32 v227, v64, v140
	v_mov_b32_dpp v0, v0 row_ror:8 row_mask:0xf bank_mask:0xf
	v_mov_b32_dpp v226, v226 row_ror:8 row_mask:0xf bank_mask:0xf
	v_mov_b32_dpp v227, v227 row_ror:8 row_mask:0xf bank_mask:0xf
	v_fmac_f32_e32 v0, v62, v140
	v_fmac_f32_e32 v226, v63, v140
	v_fmac_f32_e32 v227, v64, v140
	v_mov_b32_e32 v62, v0
	v_mov_b32_e32 v63, v226
	v_mov_b32_e32 v64, v227
	v_permlane16_swap_b32_e32 v62, v0
	v_permlane16_swap_b32_e32 v63, v226
	v_permlane16_swap_b32_e32 v64, v227
	v_add_f32_e32 v0, v62, v0
	v_add_f32_e32 v226, v63, v226
	v_add_f32_e32 v227, v64, v227
	s_and_saveexec_b64 s[0:1], s[4:5]
	ds_write_b32 v177, v0 offset:36960
	ds_write_b32 v177, v226 offset:36964
	ds_write_b32 v177, v227 offset:36968
	s_or_b64 exec, exec, s[0:1]
	v_mul_f32_e32 v0, v65, v140
	v_mul_f32_e32 v226, v34, v140
	v_mul_f32_e32 v227, v35, v140
	v_mov_b32_dpp v0, v0 row_ror:8 row_mask:0xf bank_mask:0xf
	v_mov_b32_dpp v226, v226 row_ror:8 row_mask:0xf bank_mask:0xf
	v_mov_b32_dpp v227, v227 row_ror:8 row_mask:0xf bank_mask:0xf
	v_fmac_f32_e32 v0, v65, v140
	v_fmac_f32_e32 v226, v34, v140
	v_fmac_f32_e32 v227, v35, v140
	v_mov_b32_e32 v65, v0
	v_mov_b32_e32 v34, v226
	v_mov_b32_e32 v35, v227
	v_permlane16_swap_b32_e32 v65, v0
	v_permlane16_swap_b32_e32 v34, v226
	v_permlane16_swap_b32_e32 v35, v227
	v_add_f32_e32 v0, v65, v0
	v_add_f32_e32 v226, v34, v226
	v_add_f32_e32 v227, v35, v227
	s_and_saveexec_b64 s[0:1], s[4:5]
	ds_write_b32 v177, v0 offset:36972
	ds_write_b32 v177, v226 offset:36992
	ds_write_b32 v177, v227 offset:36996
	s_or_b64 exec, exec, s[0:1]
	v_mul_f32_e32 v0, v36, v140
	v_mul_f32_e32 v226, v37, v140
	v_mul_f32_e32 v227, v38, v140
	v_mov_b32_dpp v0, v0 row_ror:8 row_mask:0xf bank_mask:0xf
	v_mov_b32_dpp v226, v226 row_ror:8 row_mask:0xf bank_mask:0xf
	v_mov_b32_dpp v227, v227 row_ror:8 row_mask:0xf bank_mask:0xf
	v_fmac_f32_e32 v0, v36, v140
	v_fmac_f32_e32 v226, v37, v140
	v_fmac_f32_e32 v227, v38, v140
	v_mov_b32_e32 v36, v0
	v_mov_b32_e32 v37, v226
	v_mov_b32_e32 v38, v227
	v_permlane16_swap_b32_e32 v36, v0
	v_permlane16_swap_b32_e32 v37, v226
	v_permlane16_swap_b32_e32 v38, v227
	v_add_f32_e32 v0, v36, v0
	v_add_f32_e32 v226, v37, v226
	v_add_f32_e32 v227, v38, v227
	s_and_saveexec_b64 s[0:1], s[4:5]
	ds_write_b32 v177, v0 offset:37000
	ds_write_b32 v177, v226 offset:37004
	ds_write_b32 v177, v227 offset:37024
	s_or_b64 exec, exec, s[0:1]
	v_mul_f32_e32 v0, v39, v140
	v_mul_f32_e32 v226, v40, v140
	v_mul_f32_e32 v227, v41, v140
	v_mov_b32_dpp v0, v0 row_ror:8 row_mask:0xf bank_mask:0xf
	v_mov_b32_dpp v226, v226 row_ror:8 row_mask:0xf bank_mask:0xf
	v_mov_b32_dpp v227, v227 row_ror:8 row_mask:0xf bank_mask:0xf
	v_fmac_f32_e32 v0, v39, v140
	v_fmac_f32_e32 v226, v40, v140
	v_fmac_f32_e32 v227, v41, v140
	v_mov_b32_e32 v39, v0
	v_mov_b32_e32 v40, v226
	v_mov_b32_e32 v41, v227
	v_permlane16_swap_b32_e32 v39, v0
	v_permlane16_swap_b32_e32 v40, v226
	v_permlane16_swap_b32_e32 v41, v227
	v_add_f32_e32 v0, v39, v0
	v_add_f32_e32 v226, v40, v226
	v_add_f32_e32 v227, v41, v227
	s_and_saveexec_b64 s[0:1], s[4:5]
	ds_write_b32 v177, v0 offset:37028
	ds_write_b32 v177, v226 offset:37032
	ds_write_b32 v177, v227 offset:37036
	s_or_b64 exec, exec, s[0:1]
	v_mul_f32_e32 v0, v42, v140
	v_mul_f32_e32 v226, v43, v140
	v_mul_f32_e32 v227, v44, v140
	v_mov_b32_dpp v0, v0 row_ror:8 row_mask:0xf bank_mask:0xf
	v_mov_b32_dpp v226, v226 row_ror:8 row_mask:0xf bank_mask:0xf
	v_mov_b32_dpp v227, v227 row_ror:8 row_mask:0xf bank_mask:0xf
	v_fmac_f32_e32 v0, v42, v140
	v_fmac_f32_e32 v226, v43, v140
	v_fmac_f32_e32 v227, v44, v140
	v_mov_b32_e32 v42, v0
	v_mov_b32_e32 v43, v226
	v_mov_b32_e32 v44, v227
	v_permlane16_swap_b32_e32 v42, v0
	v_permlane16_swap_b32_e32 v43, v226
	v_permlane16_swap_b32_e32 v44, v227
	v_add_f32_e32 v0, v42, v0
	v_add_f32_e32 v226, v43, v226
	v_add_f32_e32 v227, v44, v227
	s_and_saveexec_b64 s[0:1], s[4:5]
	ds_write_b32 v177, v0 offset:37056
	ds_write_b32 v177, v226 offset:37060
	ds_write_b32 v177, v227 offset:37064
	s_or_b64 exec, exec, s[0:1]
	v_mul_f32_e32 v0, v45, v140
	v_mul_f32_e32 v226, v46, v140
	v_mul_f32_e32 v227, v47, v140
	v_mov_b32_dpp v0, v0 row_ror:8 row_mask:0xf bank_mask:0xf
	v_mov_b32_dpp v226, v226 row_ror:8 row_mask:0xf bank_mask:0xf
	v_mov_b32_dpp v227, v227 row_ror:8 row_mask:0xf bank_mask:0xf
	v_fmac_f32_e32 v0, v45, v140
	v_fmac_f32_e32 v226, v46, v140
	v_fmac_f32_e32 v227, v47, v140
	v_mov_b32_e32 v45, v0
	v_mov_b32_e32 v46, v226
	v_mov_b32_e32 v47, v227
	v_permlane16_swap_b32_e32 v45, v0
	v_permlane16_swap_b32_e32 v46, v226
	v_permlane16_swap_b32_e32 v47, v227
	v_add_f32_e32 v0, v45, v0
	v_add_f32_e32 v226, v46, v226
	v_add_f32_e32 v227, v47, v227
	s_and_saveexec_b64 s[0:1], s[4:5]
	ds_write_b32 v177, v0 offset:37068
	ds_write_b32 v177, v226 offset:37088
	ds_write_b32 v177, v227 offset:37092
	s_or_b64 exec, exec, s[0:1]
	v_mul_f32_e32 v0, v48, v140
	v_mul_f32_e32 v226, v49, v140
	s_nop 0
	v_mov_b32_dpp v0, v0 row_ror:8 row_mask:0xf bank_mask:0xf
	v_mov_b32_dpp v226, v226 row_ror:8 row_mask:0xf bank_mask:0xf
	v_fmac_f32_e32 v0, v48, v140
	v_fmac_f32_e32 v226, v49, v140
	v_mov_b32_e32 v48, v0
	v_mov_b32_e32 v49, v226
	s_nop 0
	v_permlane16_swap_b32_e32 v48, v0
	v_permlane16_swap_b32_e32 v49, v226
	v_add_f32_e32 v0, v48, v0
	v_add_f32_e32 v226, v49, v226
	s_and_saveexec_b64 s[0:1], s[4:5]
	ds_write_b32 v177, v0 offset:37096
	ds_write_b32 v177, v226 offset:37100
	s_or_b64 exec, exec, s[0:1]
	s_waitcnt lgkmcnt(0)
	v_cmp_eq_u32_e32 vcc, s67, v168
	s_or_b64 s[0:1], s[6:7], vcc
	v_cmp_eq_u32_e32 vcc, s67, v207
	s_or_b64 vcc, s[0:1], vcc
	v_cmp_lt_i32_e64 s[0:1], s67, v168
	ds_read_b32 v0, v206 offset:36864
	ds_read_b32 v34, v206 offset:37120
	ds_read_b32 v35, v206 offset:37376
	ds_read_b32 v226, v206 offset:37632
	s_mov_b32 s28, 0
	s_mov_b32 s29, 0
	s_mov_b32 s30, 0
	s_mov_b32 s31, 0
	s_mov_b32 s18, 0x40000000
	s_waitcnt lgkmcnt(0)
	v_cndmask_b32_e32 v0, v0, v231, vcc
	v_cndmask_b32_e32 v34, v34, v231, vcc
	v_cndmask_b32_e32 v35, v35, v231, vcc
	v_cndmask_b32_e32 v226, v226, v231, vcc
	v_and_b32_e32 v0, 0x7fffffff, v0
	v_and_b32_e32 v34, 0x7fffffff, v34
	v_and_b32_e32 v35, 0x7fffffff, v35
	v_and_b32_e32 v226, 0x7fffffff, v226
	v_cndmask_b32_e64 v0, v0, -1.0, s[0:1]
	v_cndmask_b32_e64 v34, v34, -1.0, s[0:1]
	v_cndmask_b32_e64 v35, v35, -1.0, s[0:1]
	v_cndmask_b32_e64 v226, v226, -1.0, s[0:1]
